# adds GEMM-phase prologue change: K-tile 1 staging loads issued right behind K-tile 0 loads (one exposed latency per phase start instead of two)
# baseline (speedup 1.0000x reference)
.LBB0_133:
	s_mov_b32 s75, s35
	v_writelane_b32 v254, s74, 21
	v_and_b32_e32 v241, 63, v240
	s_andn2_b64 vcc, exec, s[0:1]
	v_writelane_b32 v254, s75, 22
	s_cbranch_vccnz .LBB0_449
	v_mov_b32_e32 v0, v81
	v_readlane_b32 s0, v251, 7
	v_mbcnt_lo_u32_b32 v0, -1, v0
	v_mbcnt_hi_u32_b32 v0, -1, v0
	v_add_u32_e32 v0, s69, v0
	v_readlane_b32 s1, v251, 8
	s_andn2_b64 vcc, exec, s[0:1]
	v_readfirstlane_b32 s0, v0
	s_cbranch_vccnz .LBB0_370
	s_ashr_i32 s4, s0, 6
	s_lshl_b32 s2, s4, 10
	v_readlane_b32 s6, v254, 19
	v_readlane_b32 s7, v254, 20
	s_add_i32 s31, s2, 0x100
	v_lshlrev_b32_e32 v242, 4, v0
	s_and_b32 s57, s7, 0xffff
	s_mov_b32 s56, s6
	s_add_i32 s51, s31, 0x10000
	v_readlane_b32 s2, v253, 29
	s_mov_b32 m0, s51
	s_nop 0
	buffer_load_dwordx4 v242, s[56:59], s2 offen lds
	v_add_u32_e32 v243, 0x2000, v242
	s_add_i32 s52, s31, 0x12000
	s_mov_b32 m0, s52
	s_nop 0
	buffer_load_dwordx4 v243, s[56:59], s2 offen lds
	s_add_i32 s53, s31, 0x14000
	v_readlane_b32 s2, v253, 23
	s_mov_b32 m0, s53
	s_nop 0
	buffer_load_dwordx4 v242, s[56:59], s2 offen lds
	s_add_i32 s55, s31, 0x16000
	s_mov_b32 m0, s55
	s_nop 0
	buffer_load_dwordx4 v243, s[56:59], s2 offen lds
	v_readlane_b32 s2, v253, 27
	s_mov_b32 m0, s31
	s_nop 0
	buffer_load_dwordx4 v242, s[24:27], s2 offen lds
	s_ashr_i32 s1, s0, 8
	s_add_i32 s68, s31, 0x2000
	s_mov_b32 m0, s68
	s_nop 0
	buffer_load_dwordx4 v243, s[24:27], s2 offen lds
	s_add_i32 s69, s31, 0x4000
	s_add_i32 s70, s31, 0x6000
	v_readlane_b32 s5, v253, 25
	s_mov_b32 m0, s69
	s_nop 0
	buffer_load_dwordx4 v242, s[24:27], s5 offen lds
	s_cmp_eq_u32 s1, 1
	s_cselect_b64 s[2:3], -1, 0
	s_mov_b32 m0, s70
	s_nop 0
	buffer_load_dwordx4 v243, s[24:27], s5 offen lds
	v_readlane_b32 s32, v253, 26
	v_readlane_b32 s98, v253, 28
	v_readlane_b32 s99, v253, 30
	s_nop 2
	s_add_i32 m0, s31, 0x18000
	s_nop 0
	buffer_load_dwordx4 v242, s[56:59], s32 offen lds
	s_add_i32 m0, s31, 0x1a000
	s_nop 0
	buffer_load_dwordx4 v243, s[56:59], s32 offen lds
	s_add_i32 m0, s31, 0x8000
	s_nop 0
	buffer_load_dwordx4 v242, s[24:27], s98 offen lds
	s_add_i32 m0, s31, 0xa000
	s_nop 0
	buffer_load_dwordx4 v243, s[24:27], s98 offen lds
	s_add_i32 m0, s31, 0x1c000
	s_nop 0
	buffer_load_dwordx4 v242, s[56:59], s99 offen lds
	s_add_i32 m0, s31, 0x1e000
	s_nop 0
	buffer_load_dwordx4 v243, s[56:59], s99 offen lds
	v_writelane_b32 v254, s2, 23
	s_movk_i32 s28, 0x3c0
	s_cmp_lg_u32 s1, 1
	v_writelane_b32 v254, s3, 24
	s_cbranch_scc1 .LBB0_137
	s_barrier
.LBB0_137:
	s_lshl_b32 s34, s74, 15
	v_readlane_b32 s76, v250, 39
	s_lshl_b64 s[6:7], s[34:35], 3
	v_readlane_b32 s5, v250, 22
	v_readlane_b32 s80, v250, 43
	v_readlane_b32 s81, v250, 44
	s_add_u32 s71, s5, s6
	v_readlane_b32 s5, v250, 23
	s_mul_i32 s34, s74, 0x1e00
	v_readlane_b32 s82, v250, 45
	v_readlane_b32 s83, v250, 46
	v_readlane_b32 s84, v250, 47
	v_readlane_b32 s85, v250, 48
	v_readlane_b32 s86, v250, 49
	v_readlane_b32 s87, v250, 50
	v_readlane_b32 s88, v250, 51
	v_readlane_b32 s89, v250, 52
	v_readlane_b32 s90, v250, 53
	v_readlane_b32 s91, v250, 54
	s_mov_b64 s[8:9], s[80:81]
	s_addc_u32 s72, s5, s7
	s_lshl_b64 s[6:7], s[34:35], 2
	s_mov_b64 s[12:13], s[84:85]
	s_mov_b64 s[10:11], s[82:83]
	s_add_u32 s8, s12, s6
	s_waitcnt lgkmcnt(0)
	v_and_b32_e32 v1, 15, v0
	s_addc_u32 s9, s13, s7
	s_lshl_b64 s[6:7], s[74:75], 18
	v_readlane_b32 s10, v251, 3
	v_bfe_u32 v2, v0, 4, 2
	v_lshl_or_b32 v82, s1, 6, v1
	v_readlane_b32 s11, v251, 4
	s_add_u32 s6, s10, s6
	v_lshlrev_b32_e32 v184, 6, v82
	v_lshlrev_b32_e32 v4, 4, v2
	v_lshlrev_b32_e32 v0, 2, v0
	s_addc_u32 s7, s11, s7
	s_and_b32 s4, s4, 3
	s_lshl_b32 s1, s1, 13
	v_and_or_b32 v5, v184, s28, v4
	v_and_b32_e32 v0, 32, v0
	v_bitop3_b32 v5, v5, s1, v0 bitop3:0xde
	s_lshl_b32 s1, s4, 12
	v_lshl_or_b32 v6, v1, 6, v4
	v_bitop3_b32 v0, v6, s1, v0 bitop3:0xde
	s_waitcnt vmcnt(8)
	s_barrier
	s_add_i32 s73, s31, 0x18000
	v_readlane_b32 s1, v253, 26
	v_readlane_b32 s77, v250, 40
	v_readlane_b32 s78, v250, 41
	v_readlane_b32 s79, v250, 42
	s_add_i32 s74, s31, 0x1a000
	s_add_i32 s75, s31, 0x8000
	v_readlane_b32 s1, v253, 28
	s_add_i32 s76, s31, 0xa000
	s_add_i32 s77, s31, 0x1c000
	s_add_i32 s78, s31, 0x1e000
	s_add_i32 s79, s31, 0xc000
	s_cmpk_lt_u32 s0, 0x100
	v_readlane_b32 s1, v253, 30
	s_cselect_b64 s[10:11], -1, 0
	s_bitcmp0_b32 s0, 6
	s_cselect_b64 s[12:13], -1, 0
	s_and_b32 s0, s0, 0xfffff00
	s_lshl_b32 s1, s4, 6
	s_waitcnt vmcnt(6)
	s_or_b32 s0, s1, s0
	s_mov_b64 s[14:15], s[86:87]
	s_waitcnt lgkmcnt(0)
	v_lshlrev_b32_e32 v3, 3, v2
	v_mov_b32_e32 v83, v81
	v_or3_b32 v1, s0, v4, v1
	v_readlane_b32 s0, v253, 24
	s_mov_b64 s[16:17], s[88:89]
	s_mov_b64 s[18:19], s[90:91]
	s_mov_b32 s82, 0
	v_lshlrev_b32_e32 v186, 3, v82
	v_lshl_or_b32 v244, s4, 5, v3
	v_mov_b32_e32 v187, v81
	v_mov_b32_e32 v185, v81
	v_cmp_eq_u32_e64 s[36:37], 0, v2
	v_cmp_gt_u32_e64 s[38:39], 2, v2
	v_lshlrev_b32_e32 v188, 4, v1
	v_mov_b32_e32 v189, v81
	s_add_i32 s83, s31, 0xe000
	v_lshl_add_u64 v[190:191], v[82:83], 4, s[6:7]
	v_add_u32_e32 v83, 0x100, v0
	v_add_u32_e32 v245, 0x100, v5
	v_readlane_b32 s15, v253, 22
	s_mov_b32 s14, s0
	v_readlane_b32 s5, v253, 29
	v_readlane_b32 s4, v253, 27
	s_barrier
	s_branch .LBB0_140

.LBB0_580:
	s_andn2_b64 vcc, exec, s[0:1]
	v_readlane_b32 s0, v252, 47
	v_readlane_b32 s1, v252, 48
	s_nop 1
	v_cndmask_b32_e64 v0, 0, 1, s[0:1]
	v_cmp_ne_u32_e64 s[80:81], 1, v0
	s_cbranch_vccnz .LBB0_675
	v_mov_b32_e32 v0, v81
	s_and_b64 vcc, exec, s[80:81]
	v_mbcnt_lo_u32_b32 v0, -1, v0
	v_mbcnt_hi_u32_b32 v0, -1, v0
	v_add_u32_e32 v0, s69, v0
	s_nop 0
	v_readfirstlane_b32 s0, v0
	s_cbranch_vccnz .LBB0_603
	v_writelane_b32 v254, s80, 47
	v_lshlrev_b32_e32 v224, 4, v0
	s_mov_b32 s51, s59
	v_writelane_b32 v254, s81, 48
	v_add_u32_e32 v225, 0x2000, v224
	v_readlane_b32 s2, v254, 19
	v_readlane_b32 s3, v254, 20
	s_add_u32 s48, s2, 0x1e00000
	s_addc_u32 s4, s3, 0
	s_ashr_i32 s1, s0, 6
	s_lshl_b32 s2, s1, 10
	s_add_i32 s31, s2, 0x100
	s_and_b32 s49, s4, 0xffff
	s_add_i32 s34, s31, 0x10000
	v_readlane_b32 s4, v253, 11
	s_mov_b32 m0, s34
	s_nop 0
	buffer_load_dwordx4 v224, s[48:51], s4 offen lds
	s_add_i32 s55, s31, 0x12000
	s_mov_b32 m0, s55
	s_nop 0
	buffer_load_dwordx4 v225, s[48:51], s4 offen lds
	s_ashr_i32 s3, s0, 8
	s_add_i32 s72, s31, 0x14000
	v_readlane_b32 s4, v253, 5
	s_mov_b32 m0, s72
	s_nop 0
	buffer_load_dwordx4 v224, s[48:51], s4 offen lds
	s_add_i32 s73, s31, 0x16000
	s_add_i32 s74, s31, 0x2000
	s_add_i32 s75, s31, 0x4000
	s_add_i32 s76, s31, 0x6000
	s_mov_b32 m0, s73
	s_nop 0
	buffer_load_dwordx4 v225, s[48:51], s4 offen lds
	v_readlane_b32 s4, v254, 6
	s_cmp_eq_u32 s3, 1
	v_readlane_b32 s6, v254, 8
	v_readlane_b32 s7, v254, 9
	s_cselect_b64 s[10:11], -1, 0
	v_readlane_b32 s5, v254, 7
	s_mov_b32 s6, s26
	s_mov_b32 s7, s27
	v_readlane_b32 s8, v253, 9
	s_mov_b32 m0, s31
	s_nop 0
	buffer_load_dwordx4 v224, s[4:7], s8 offen lds
	v_writelane_b32 v254, s10, 45
	s_mov_b32 m0, s74
	s_nop 0
	buffer_load_dwordx4 v225, s[4:7], s8 offen lds
	v_readlane_b32 s8, v253, 7
	s_mov_b32 m0, s75
	s_nop 0
	buffer_load_dwordx4 v224, s[4:7], s8 offen lds
	s_cmp_lg_u32 s3, 1
	v_writelane_b32 v254, s11, 46
	v_writelane_b32 v254, s4, 6
	s_mov_b32 m0, s76
	s_nop 0
	buffer_load_dwordx4 v225, s[4:7], s8 offen lds
	s_cselect_b32 s100, 1, 0
	v_readlane_b32 s32, v253, 8
	v_readlane_b32 s98, v253, 10
	v_readlane_b32 s99, v253, 12
	s_nop 2
	s_add_i32 m0, s31, 0x18000
	s_nop 0
	buffer_load_dwordx4 v224, s[48:51], s32 offen lds
	s_add_i32 m0, s31, 0x1a000
	s_nop 0
	buffer_load_dwordx4 v225, s[48:51], s32 offen lds
	s_add_i32 m0, s31, 0x8000
	s_nop 0
	buffer_load_dwordx4 v224, s[4:7], s98 offen lds
	s_add_i32 m0, s31, 0xa000
	s_nop 0
	buffer_load_dwordx4 v225, s[4:7], s98 offen lds
	s_add_i32 m0, s31, 0x1c000
	s_nop 0
	buffer_load_dwordx4 v224, s[48:51], s99 offen lds
	s_add_i32 m0, s31, 0x1e000
	s_nop 0
	buffer_load_dwordx4 v225, s[48:51], s99 offen lds
	s_cmp_lg_u32 s100, 0
	s_nop 1
	v_writelane_b32 v254, s5, 7
	v_writelane_b32 v254, s6, 8
	v_writelane_b32 v254, s7, 9
	s_cbranch_scc1 .LBB0_584
	s_barrier
.LBB0_584:
	s_waitcnt lgkmcnt(0)
	v_and_b32_e32 v1, 15, v0
	s_and_b32 s4, s1, 3
	v_and_b32_e32 v2, 48, v0
	s_waitcnt lgkmcnt(0)
	v_lshlrev_b32_e32 v3, 6, v1
	v_lshlrev_b32_e32 v0, 2, v0
	s_lshl_b32 s3, s3, 13
	v_or_b32_e32 v4, v3, v2
	v_and_b32_e32 v0, 32, v0
	s_lshl_b32 s5, s4, 12
	v_bitop3_b32 v3, v3, v0, v2 bitop3:0x36
	v_bitop3_b32 v5, v4, s3, v0 bitop3:0xde
	v_bitop3_b32 v0, v4, s5, v0 bitop3:0xde
	s_waitcnt vmcnt(8)
	s_barrier
	s_add_i32 s77, s31, 0x18000
	v_readlane_b32 s5, v253, 8
	s_add_i32 s78, s31, 0x1a000
	v_readlane_b32 s8, v254, 6
	s_add_i32 s79, s31, 0x8000
	v_readlane_b32 s9, v254, 7
	v_readlane_b32 s10, v254, 8
	v_readlane_b32 s11, v254, 9
	v_readlane_b32 s5, v253, 10
	s_add_i32 s82, s31, 0xa000
	s_add_i32 s83, s31, 0x1c000
	v_readlane_b32 s5, v253, 12
	s_add_i32 s84, s31, 0x1e000
	s_and_b32 s5, s0, 0xfffff00
	s_lshl_b32 s4, s4, 6
	s_or_b32 s4, s4, s5
	s_add_i32 s85, s31, 0xc000
	s_cmpk_lt_u32 s0, 0x100
	v_or3_b32 v1, s4, v2, v1
	s_cselect_b64 s[4:5], -1, 0
	s_lshl_b32 s0, s1, 13
	s_and_b32 s1, s2, 0x400
	s_waitcnt vmcnt(6)
	s_or_b32 s1, s3, s1
	v_lshlrev_b32_e32 v220, 4, v1
	v_writelane_b32 v254, s4, 43
	s_and_b32 s0, s0, 0x4000
	v_or_b32_e32 v1, s1, v3
	v_mov_b32_e32 v221, v81
	v_writelane_b32 v254, s5, 44
	v_add_u32_e32 v222, s0, v1
	v_mov_b32_e32 v223, v81
	s_add_i32 s86, s31, 0xe000
	s_mov_b32 s87, 0
	v_add_u32_e32 v226, 0x100, v0
	v_add_u32_e32 v227, 0x100, v5
	v_readlane_b32 s92, v253, 4
	v_readlane_b32 s0, v253, 6
	v_readlane_b32 s38, v253, 11
	v_readlane_b32 s96, v253, 9
	s_barrier
	s_branch .LBB0_587

.LBB0_677:
	s_andn2_b64 vcc, exec, s[0:1]
	s_cbranch_vccnz .LBB0_783
	v_mov_b32_e32 v0, v81
	s_and_b64 vcc, exec, s[80:81]
	v_mbcnt_lo_u32_b32 v0, -1, v0
	v_mbcnt_hi_u32_b32 v0, -1, v0
	v_add_u32_e32 v0, s69, v0
	s_nop 0
	v_readfirstlane_b32 s2, v0
	s_cbranch_vccnz .LBB0_714
	v_readlane_b32 s0, v254, 19
	v_readlane_b32 s1, v254, 20
	s_add_u32 s48, s0, 0x2600000
	s_addc_u32 s0, s1, 0
	s_ashr_i32 s4, s2, 6
	s_lshl_b32 s5, s4, 10
	s_add_i32 s31, s5, 0x100
	s_waitcnt lgkmcnt(0)
	v_lshlrev_b32_e32 v220, 4, v0
	s_and_b32 s49, s0, 0xffff
	s_mov_b32 s51, s59
	s_add_i32 s55, s31, 0x10000
	v_readlane_b32 s0, v253, 36
	s_mov_b32 m0, s55
	s_nop 0
	buffer_load_dwordx4 v220, s[48:51], s0 offen lds
	v_add_u32_e32 v221, 0x2000, v220
	s_add_i32 s76, s31, 0x12000
	s_mov_b32 m0, s76
	s_nop 0
	buffer_load_dwordx4 v221, s[48:51], s0 offen lds
	s_add_i32 s77, s31, 0x14000
	v_readlane_b32 s0, v253, 31
	s_mov_b32 m0, s77
	s_nop 0
	buffer_load_dwordx4 v220, s[48:51], s0 offen lds
	v_readlane_b32 s8, v254, 10
	s_add_i32 s78, s31, 0x16000
	s_mov_b32 m0, s78
	s_nop 0
	buffer_load_dwordx4 v221, s[48:51], s0 offen lds
	v_readlane_b32 s10, v254, 12
	v_readlane_b32 s11, v254, 13
	v_readlane_b32 s9, v254, 11
	s_mov_b32 s10, s26
	s_mov_b32 s11, s27
	v_readlane_b32 s0, v253, 34
	s_mov_b32 m0, s31
	s_nop 0
	buffer_load_dwordx4 v220, s[8:11], s0 offen lds
	s_add_i32 s79, s31, 0x2000
	s_mov_b32 m0, s79
	s_nop 0
	buffer_load_dwordx4 v221, s[8:11], s0 offen lds
	s_add_i32 s82, s31, 0x4000
	v_readlane_b32 s6, v253, 32
	s_mov_b32 m0, s82
	s_nop 0
	buffer_load_dwordx4 v220, s[8:11], s6 offen lds
	v_writelane_b32 v254, s8, 10
	s_ashr_i32 s3, s2, 8
	s_add_i32 s83, s31, 0x6000
	v_writelane_b32 v254, s9, 11
	s_mov_b32 m0, s83
	s_nop 0
	buffer_load_dwordx4 v221, s[8:11], s6 offen lds
	v_readlane_b32 s32, v253, 33
	v_readlane_b32 s98, v253, 35
	v_readlane_b32 s99, v253, 37
	s_nop 2
	s_add_i32 m0, s31, 0x18000
	s_nop 0
	buffer_load_dwordx4 v220, s[48:51], s32 offen lds
	s_add_i32 m0, s31, 0x1a000
	s_nop 0
	buffer_load_dwordx4 v221, s[48:51], s32 offen lds
	s_add_i32 m0, s31, 0x8000
	s_nop 0
	buffer_load_dwordx4 v220, s[8:11], s98 offen lds
	s_add_i32 m0, s31, 0xa000
	s_nop 0
	buffer_load_dwordx4 v221, s[8:11], s98 offen lds
	s_add_i32 m0, s31, 0x1c000
	s_nop 0
	buffer_load_dwordx4 v220, s[48:51], s99 offen lds
	s_add_i32 m0, s31, 0x1e000
	s_nop 0
	buffer_load_dwordx4 v221, s[48:51], s99 offen lds
	s_cmp_eq_u32 s3, 1
	v_writelane_b32 v254, s10, 12
	s_cselect_b64 s[0:1], -1, 0
	s_cmp_lg_u32 s3, 1
	v_writelane_b32 v254, s11, 13
	s_cbranch_scc1 .LBB0_681
	s_barrier
.LBB0_681:
	v_readlane_b32 s6, v254, 21
	v_readlane_b32 s7, v254, 22
	s_lshl_b32 s34, s6, 15
	s_lshl_b64 s[6:7], s[34:35], 3
	v_readlane_b32 s8, v250, 22
	s_add_u32 s6, s8, s6
	v_readlane_b32 s8, v250, 23
	v_bfe_u32 v1, v0, 4, 2
	s_addc_u32 s7, s8, s7
	s_and_b32 s8, s4, 3
	v_and_b32_e32 v3, 15, v0
	v_lshlrev_b32_e32 v4, 4, v1
	v_lshlrev_b32_e32 v0, 2, v0
	v_lshl_or_b32 v2, s3, 6, v3
	s_lshl_b32 s9, s3, 13
	v_lshl_or_b32 v3, v3, 6, v4
	v_and_b32_e32 v0, 32, v0
	s_lshl_b32 s3, s8, 12
	v_bitop3_b32 v5, v3, s3, v0 bitop3:0xde
	s_waitcnt vmcnt(8)
	s_barrier
	s_add_i32 s34, s31, 0x18000
	v_readlane_b32 s3, v253, 33
	s_add_i32 s84, s31, 0x1a000
	v_readlane_b32 s12, v254, 10
	s_add_i32 s85, s31, 0x8000
	v_readlane_b32 s13, v254, 11
	v_readlane_b32 s14, v254, 12
	v_readlane_b32 s15, v254, 13
	v_readlane_b32 s3, v253, 35
	s_add_i32 s86, s31, 0xa000
	s_add_i32 s87, s31, 0x1c000
	s_add_i32 s88, s31, 0x1e000
	s_add_i32 s89, s31, 0xc000
	v_readlane_b32 s3, v253, 37
	s_cmpk_lt_u32 s2, 0x100
	s_cselect_b64 s[2:3], -1, 0
	s_lshl_b32 s4, s4, 13
	s_and_b32 s5, s5, 0x400
	s_and_b32 s4, s4, 0x4000
	s_or_b32 s5, s5, s9
	s_add_i32 s5, s5, s4
	v_bitop3_b32 v4, v3, s9, v0 bitop3:0xde
	s_waitcnt vmcnt(6)
	v_bitop3_b32 v80, s5, v3, v0 bitop3:0xf6
	v_mov_b32_e32 v3, v81
	v_cmp_eq_u32_e64 s[38:39], 0, v1
	v_lshl_add_u64 v[0:1], v[2:3], 3, s[6:7]
	s_mov_b64 s[4:5], 0x20000
	s_mov_b32 s90, 0
	s_add_i32 s91, s31, 0xe000
	v_lshl_add_u64 v[82:83], v[0:1], 0, s[4:5]
	v_add_u32_e32 v222, 0x100, v5
	v_add_u32_e32 v223, 0x100, v4
	v_readlane_b32 s5, v253, 38
	v_readlane_b32 s4, v253, 40
	v_readlane_b32 s9, v253, 36
	v_readlane_b32 s8, v253, 34
	s_barrier
	s_branch .LBB0_684

.LBB0_785:
	s_andn2_b64 vcc, exec, s[0:1]
	s_cbranch_vccnz .LBB0_871
	v_mov_b32_e32 v0, v81
	v_readlane_b32 s0, v252, 50
	v_mbcnt_lo_u32_b32 v0, -1, v0
	v_mbcnt_hi_u32_b32 v0, -1, v0
	v_add_u32_e32 v0, s69, v0
	v_readlane_b32 s1, v252, 51
	s_andn2_b64 vcc, exec, s[0:1]
	v_readfirstlane_b32 s2, v0
	s_cbranch_vccnz .LBB0_802
	v_readlane_b32 s0, v254, 19
	v_readlane_b32 s1, v254, 20
	s_add_u32 s28, s0, 0x2e00000
	s_addc_u32 s0, s1, 0
	s_ashr_i32 s4, s2, 6
	s_lshl_b32 s33, s4, 10
	s_add_i32 s6, s33, 0x100
	v_lshlrev_b32_e32 v166, 4, v0
	s_and_b32 s29, s0, 0xffff
	s_mov_b32 s31, s59
	s_add_i32 s7, s6, 0x10000
	v_readlane_b32 s0, v253, 20
	s_mov_b32 m0, s7
	s_nop 0
	buffer_load_dwordx4 v166, s[28:31], s0 offen lds
	v_add_u32_e32 v167, 0x2000, v166
	s_add_i32 s8, s6, 0x12000
	s_mov_b32 m0, s8
	s_nop 0
	buffer_load_dwordx4 v167, s[28:31], s0 offen lds
	s_add_i32 s9, s6, 0x14000
	v_readlane_b32 s0, v253, 14
	s_mov_b32 m0, s9
	s_nop 0
	buffer_load_dwordx4 v166, s[28:31], s0 offen lds
	s_add_i32 s10, s6, 0x16000
	s_mov_b32 m0, s10
	s_nop 0
	buffer_load_dwordx4 v167, s[28:31], s0 offen lds
	v_readlane_b32 s0, v253, 18
	s_mov_b32 m0, s6
	s_nop 0
	buffer_load_dwordx4 v166, s[24:27], s0 offen lds
	s_add_i32 s11, s6, 0x2000
	s_mov_b32 m0, s11
	s_nop 0
	buffer_load_dwordx4 v167, s[24:27], s0 offen lds
	s_add_i32 s12, s6, 0x4000
	v_readlane_b32 s3, v253, 16
	s_mov_b32 m0, s12
	s_nop 0
	buffer_load_dwordx4 v166, s[24:27], s3 offen lds
	s_ashr_i32 s5, s2, 8
	s_add_i32 s13, s6, 0x6000
	s_mov_b32 m0, s13
	s_nop 0
	buffer_load_dwordx4 v167, s[24:27], s3 offen lds
	v_readlane_b32 s32, v253, 17
	v_readlane_b32 s98, v253, 19
	v_readlane_b32 s99, v253, 21
	s_nop 2
	s_add_i32 m0, s6, 0x18000
	s_nop 0
	buffer_load_dwordx4 v166, s[28:31], s32 offen lds
	s_add_i32 m0, s6, 0x1a000
	s_nop 0
	buffer_load_dwordx4 v167, s[28:31], s32 offen lds
	s_add_i32 m0, s6, 0x8000
	s_nop 0
	buffer_load_dwordx4 v166, s[24:27], s98 offen lds
	s_add_i32 m0, s6, 0xa000
	s_nop 0
	buffer_load_dwordx4 v167, s[24:27], s98 offen lds
	s_add_i32 m0, s6, 0x1c000
	s_nop 0
	buffer_load_dwordx4 v166, s[28:31], s99 offen lds
	s_add_i32 m0, s6, 0x1e000
	s_nop 0
	buffer_load_dwordx4 v167, s[28:31], s99 offen lds
	s_cmp_eq_u32 s5, 1
	s_cselect_b64 s[0:1], -1, 0
	s_cmp_lg_u32 s5, 1
	s_cbranch_scc1 .LBB0_789
	s_barrier
.LBB0_789:
	s_lshl_b32 s34, s74, 15
	s_lshl_b64 s[14:15], s[34:35], 3
	v_readlane_b32 s3, v250, 22
	s_add_u32 s3, s3, s14
	v_readlane_b32 s14, v250, 23
	s_addc_u32 s15, s14, s15
	s_add_u32 s14, s3, 0x20000
	s_waitcnt lgkmcnt(0)
	v_and_b32_e32 v1, 15, v0
	s_addc_u32 s15, s15, 0
	s_and_b32 s3, s4, 3
	v_and_b32_e32 v2, 48, v0
	v_lshlrev_b32_e32 v3, 6, v1
	v_lshlrev_b32_e32 v0, 2, v0
	s_lshl_b32 s36, s5, 13
	v_or_b32_e32 v4, v3, v2
	v_and_b32_e32 v0, 32, v0
	s_lshl_b32 s3, s3, 12
	v_bitop3_b32 v2, v3, v0, v2 bitop3:0x36
	v_bitop3_b32 v3, v4, s36, v0 bitop3:0xde
	v_bitop3_b32 v0, v4, s3, v0 bitop3:0xde
	s_waitcnt vmcnt(8)
	s_barrier
	s_add_i32 s16, s6, 0x18000
	v_readlane_b32 s3, v253, 17
	s_add_i32 s17, s6, 0x1a000
	s_add_i32 s18, s6, 0x8000
	v_readlane_b32 s3, v253, 19
	s_add_i32 s19, s6, 0xa000
	s_add_i32 s34, s6, 0x1c000
	s_add_i32 s40, s6, 0x1e000
	s_add_i32 s41, s6, 0xc000
	v_readlane_b32 s3, v253, 21
	s_cmpk_lt_u32 s2, 0x100
	s_cselect_b64 s[2:3], -1, 0
	s_and_b32 s33, s33, 0x400
	v_lshlrev_b32_e32 v1, 3, v1
	s_waitcnt vmcnt(6)
	s_lshl_b32 s4, s4, 13
	v_lshl_or_b32 v80, s5, 9, v1
	s_or_b32 s5, s36, s33
	s_and_b32 s4, s4, 0x4000
	v_or_b32_e32 v1, s5, v2
	v_add_u32_e32 v82, s4, v1
	v_mov_b32_e32 v83, v81
	s_add_i32 s42, s6, 0xe000
	s_mov_b32 s43, 0
	v_add_u32_e32 v168, 0x100, v0
	v_add_u32_e32 v169, 0x100, v3
	v_readlane_b32 s36, v253, 13
	v_readlane_b32 s33, v253, 15
	v_readlane_b32 s51, v253, 20
	v_readlane_b32 s37, v253, 18
	s_barrier
	s_branch .LBB0_792

.LBB0_871:
	s_cmp_gt_i32 s90, s16
	s_cselect_b64 s[0:1], -1, 0
	s_cmp_ge_i32 s16, s91
	s_cselect_b64 s[2:3], -1, 0
	s_or_b64 s[0:1], s[0:1], s[2:3]
	s_and_b64 vcc, exec, s[0:1]
	s_cbranch_vccnz .LBB0_130
	v_mov_b32_e32 v0, v81
	s_and_b64 vcc, exec, s[80:81]
	v_mbcnt_lo_u32_b32 v0, -1, v0
	v_mbcnt_hi_u32_b32 v0, -1, v0
	v_add_u32_e32 v0, s69, v0
	s_nop 0
	v_readfirstlane_b32 s2, v0
	s_cbranch_vccnz .LBB0_908
	v_readlane_b32 s0, v254, 19
	v_readlane_b32 s1, v254, 20
	s_add_u32 s52, s0, 0x5a00000
	s_addc_u32 s0, s1, 0
	s_ashr_i32 s4, s2, 6
	s_lshl_b32 s5, s4, 10
	s_add_i32 s31, s5, 0x100
	s_waitcnt lgkmcnt(0)
	v_lshlrev_b32_e32 v220, 4, v0
	s_and_b32 s53, s0, 0xffff
	s_mov_b32 s55, s59
	s_add_i32 s51, s31, 0x10000
	v_readlane_b32 s0, v253, 45
	s_mov_b32 m0, s51
	s_nop 0
	buffer_load_dwordx4 v220, s[52:55], s0 offen lds
	v_add_u32_e32 v221, 0x2000, v220
	s_add_i32 s74, s31, 0x12000
	s_mov_b32 m0, s74
	s_nop 0
	buffer_load_dwordx4 v221, s[52:55], s0 offen lds
	s_add_i32 s75, s31, 0x14000
	v_readlane_b32 s0, v253, 39
	s_mov_b32 m0, s75
	s_nop 0
	buffer_load_dwordx4 v220, s[52:55], s0 offen lds
	s_add_i32 s76, s31, 0x16000
	s_mov_b32 m0, s76
	s_nop 0
	buffer_load_dwordx4 v221, s[52:55], s0 offen lds
	v_readlane_b32 s0, v253, 43
	s_mov_b32 m0, s31
	s_nop 0
	buffer_load_dwordx4 v220, s[20:23], s0 offen lds
	s_add_i32 s77, s31, 0x2000
	s_mov_b32 m0, s77
	s_nop 0
	buffer_load_dwordx4 v221, s[20:23], s0 offen lds
	s_add_i32 s78, s31, 0x4000
	v_readlane_b32 s6, v253, 41
	s_mov_b32 m0, s78
	s_nop 0
	buffer_load_dwordx4 v220, s[20:23], s6 offen lds
	s_ashr_i32 s3, s2, 8
	s_add_i32 s79, s31, 0x6000
	s_mov_b32 m0, s79
	s_nop 0
	buffer_load_dwordx4 v221, s[20:23], s6 offen lds
	v_readlane_b32 s32, v253, 42
	v_readlane_b32 s98, v253, 44
	v_readlane_b32 s99, v253, 46
	s_nop 2
	s_add_i32 m0, s31, 0x18000
	s_nop 0
	buffer_load_dwordx4 v220, s[52:55], s32 offen lds
	s_add_i32 m0, s31, 0x1a000
	s_nop 0
	buffer_load_dwordx4 v221, s[52:55], s32 offen lds
	s_add_i32 m0, s31, 0x8000
	s_nop 0
	buffer_load_dwordx4 v220, s[20:23], s98 offen lds
	s_add_i32 m0, s31, 0xa000
	s_nop 0
	buffer_load_dwordx4 v221, s[20:23], s98 offen lds
	s_add_i32 m0, s31, 0x1c000
	s_nop 0
	buffer_load_dwordx4 v220, s[52:55], s99 offen lds
	s_add_i32 m0, s31, 0x1e000
	s_nop 0
	buffer_load_dwordx4 v221, s[52:55], s99 offen lds
	s_cmp_eq_u32 s3, 1
	s_cselect_b64 s[0:1], -1, 0
	s_cmp_lg_u32 s3, 1
	s_cbranch_scc1 .LBB0_875
	s_barrier
.LBB0_875:
	v_readlane_b32 s6, v254, 21
	v_readlane_b32 s7, v254, 22
	s_lshl_b32 s34, s6, 15
	s_lshl_b64 s[6:7], s[34:35], 3
	v_readlane_b32 s8, v250, 22
	s_add_u32 s6, s8, s6
	v_readlane_b32 s8, v250, 23
	v_bfe_u32 v1, v0, 4, 2
	s_addc_u32 s7, s8, s7
	s_and_b32 s8, s4, 3
	v_and_b32_e32 v3, 15, v0
	v_lshlrev_b32_e32 v4, 4, v1
	v_lshlrev_b32_e32 v0, 2, v0
	v_lshl_or_b32 v2, s3, 6, v3
	s_lshl_b32 s9, s3, 13
	v_lshl_or_b32 v3, v3, 6, v4
	v_and_b32_e32 v0, 32, v0
	s_lshl_b32 s3, s8, 12
	v_bitop3_b32 v5, v3, s3, v0 bitop3:0xde
	s_waitcnt vmcnt(8)
	s_barrier
	s_add_i32 s34, s31, 0x18000
	v_readlane_b32 s3, v253, 42
	s_add_i32 s82, s31, 0x1a000
	s_add_i32 s83, s31, 0x8000
	v_readlane_b32 s3, v253, 44
	s_add_i32 s84, s31, 0xa000
	s_add_i32 s85, s31, 0x1c000
	s_add_i32 s86, s31, 0x1e000
	s_add_i32 s87, s31, 0xc000
	v_readlane_b32 s3, v253, 46
	s_cmpk_lt_u32 s2, 0x100
	s_cselect_b64 s[2:3], -1, 0
	s_lshl_b32 s4, s4, 13
	s_and_b32 s5, s5, 0x400
	s_and_b32 s4, s4, 0x4000
	s_or_b32 s5, s5, s9
	s_add_i32 s5, s5, s4
	v_bitop3_b32 v4, v3, s9, v0 bitop3:0xde
	s_waitcnt vmcnt(6)
	v_bitop3_b32 v80, s5, v3, v0 bitop3:0xf6
	v_mov_b32_e32 v3, v81
	v_cmp_eq_u32_e64 s[36:37], 0, v1
	v_lshl_add_u64 v[0:1], v[2:3], 3, s[6:7]
	s_mov_b64 s[4:5], 0x40000
	s_mov_b32 s88, 0
	s_add_i32 s89, s31, 0xe000
	v_lshl_add_u64 v[82:83], v[0:1], 0, s[4:5]
	v_add_u32_e32 v222, 0x100, v5
	v_add_u32_e32 v223, 0x100, v4
	v_readlane_b32 s5, v253, 38
	v_readlane_b32 s4, v253, 40
	v_readlane_b32 s9, v253, 45
	v_readlane_b32 s8, v253, 43
	s_barrier
	s_branch .LBB0_878

	.amdhsa_kernel _Z3fwd4Args
		.amdhsa_group_segment_fixed_size 256
		.amdhsa_private_segment_fixed_size 0
		.amdhsa_kernarg_size 424
		.amdhsa_user_sgpr_count 2
		.amdhsa_user_sgpr_dispatch_ptr 0
		.amdhsa_user_sgpr_queue_ptr 0
		.amdhsa_user_sgpr_kernarg_segment_ptr 1
		.amdhsa_user_sgpr_dispatch_id 0
		.amdhsa_user_sgpr_kernarg_preload_length 0
		.amdhsa_user_sgpr_kernarg_preload_offset 0
		.amdhsa_user_sgpr_private_segment_size 0
		.amdhsa_uses_dynamic_stack 0
		.amdhsa_enable_private_segment 0
		.amdhsa_system_sgpr_workgroup_id_x 1
		.amdhsa_system_sgpr_workgroup_id_y 0
		.amdhsa_system_sgpr_workgroup_id_z 0
		.amdhsa_system_sgpr_workgroup_info 0
		.amdhsa_system_vgpr_workitem_id 2
		.amdhsa_next_free_vgpr 256
		.amdhsa_next_free_sgpr 102
		.amdhsa_accum_offset 256
		.amdhsa_reserve_vcc 1
		.amdhsa_float_round_mode_32 0
		.amdhsa_float_round_mode_16_64 0
		.amdhsa_float_denorm_mode_32 3
		.amdhsa_float_denorm_mode_16_64 3
		.amdhsa_dx10_clamp 1
		.amdhsa_ieee_mode 1
		.amdhsa_fp16_overflow 0
		.amdhsa_tg_split 0
		.amdhsa_exception_fp_ieee_invalid_op 0
		.amdhsa_exception_fp_denorm_src 0
		.amdhsa_exception_fp_ieee_div_zero 0
		.amdhsa_exception_fp_ieee_overflow 0
		.amdhsa_exception_fp_ieee_underflow 0
		.amdhsa_exception_fp_ieee_inexact 0
		.amdhsa_exception_int_div_zero 0
	.end_amdhsa_kernel

amdhsa.kernels:
  - .agpr_count:     0
    .args:
      - .offset:         0
        .size:           168
        .value_kind:     by_value
      - .offset:         168
        .size:           4
        .value_kind:     hidden_block_count_x
      - .offset:         172
        .size:           4
        .value_kind:     hidden_block_count_y
      - .offset:         176
        .size:           4
        .value_kind:     hidden_block_count_z
      - .offset:         180
        .size:           2
        .value_kind:     hidden_group_size_x
      - .offset:         182
        .size:           2
        .value_kind:     hidden_group_size_y
      - .offset:         184
        .size:           2
        .value_kind:     hidden_group_size_z
      - .offset:         186
        .size:           2
        .value_kind:     hidden_remainder_x
      - .offset:         188
        .size:           2
        .value_kind:     hidden_remainder_y
      - .offset:         190
        .size:           2
        .value_kind:     hidden_remainder_z
      - .offset:         208
        .size:           8
        .value_kind:     hidden_global_offset_x
      - .offset:         216
        .size:           8
        .value_kind:     hidden_global_offset_y
      - .offset:         224
        .size:           8
        .value_kind:     hidden_global_offset_z
      - .offset:         232
        .size:           2
        .value_kind:     hidden_grid_dims
      - .offset:         288
        .size:           4
        .value_kind:     hidden_dynamic_lds_size
    .group_segment_fixed_size: 256
    .kernarg_segment_align: 8
    .kernarg_segment_size: 424
    .language:       OpenCL C
    .language_version:
      - 2
      - 0
    .max_flat_workgroup_size: 512
    .name:           _Z3fwd4Args
    .private_segment_fixed_size: 0
    .sgpr_count:     108
    .sgpr_spill_count: 362
    .symbol:         _Z3fwd4Args.kd
    .uniform_work_group_size: 1
    .uses_dynamic_stack: false
    .vgpr_count:     256
    .vgpr_spill_count: 0
    .wavefront_size: 64
